# group-local (blockIdx&7) barriers at GEMM->GEMM syncs 4,5,9,10 (data flow is group-local) + ssin-from-LDS in IN0 epilogue
# speedup vs baseline: 1.0127x; 1.0127x over previous
.LBB0_324:
.LBB0_325:
	v_and_b32_e32 v1, 0x3fffffff, v0
	v_cmp_eq_u32_e32 vcc, 0, v1
	s_waitcnt vmcnt(0)
	s_barrier
	s_and_saveexec_b64 s[6:7], vcc
	s_cbranch_execz .LBB0_335
	buffer_wbl2 sc1
	s_waitcnt vmcnt(0)
	s_load_dwordx2 s[8:9], s[0:1], 0xc8
	s_load_dword s3, s[0:1], 0x1b8
	s_and_b32 s10, s2, 7
	v_mov_b32_e32 v2, 1
	s_waitcnt lgkmcnt(0)
	s_add_u32 s8, s8, 0x2a4000
	s_addc_u32 s9, s9, 0
	s_sub_u32 s12, s3, s10
	s_add_u32 s12, s12, 7
	s_lshr_b32 s12, s12, 3
	s_mul_i32 s12, s12, 3
	s_min_u32 s3, s3, 8
	s_mul_i32 s3, s3, 2
	s_lshl_b32 s10, s10, 10
	v_mov_b32_e32 v1, s10
	global_atomic_add v3, v1, v2, s[8:9] sc0
	s_waitcnt vmcnt(0)
	v_readfirstlane_b32 s11, v3
	s_nop 3
	s_add_u32 s11, s11, 1
	s_cmp_lg_u32 s11, s12
	s_cbranch_scc1 .Lfs_wait_4
	s_branch .Lfs_grel_4
	v_mov_b32_e32 v1, 0x4000
	global_atomic_add v3, v1, v2, s[8:9] sc0
	s_waitcnt vmcnt(0)
	v_readfirstlane_b32 s11, v3
	s_nop 3
	s_add_u32 s11, s11, 1
	v_mov_b32_e32 v1, 0x5000
	s_cmp_lg_u32 s11, s3
	s_cbranch_scc1 .Lfs_topspin_4
	global_atomic_add v1, v2, s[8:9]
	s_branch .Lfs_grel_4
.Lfs_topspin_4:
	s_sleep 1
	global_load_dword v3, v1, s[8:9] sc1
	s_waitcnt vmcnt(0)
	v_readfirstlane_b32 s11, v3
	s_nop 3
	s_cmp_lt_u32 s11, 2
	s_cbranch_scc1 .Lfs_topspin_4

.LBB0_342:
.LBB0_343:
	v_and_b32_e32 v1, 0x3fffffff, v0
	v_cmp_eq_u32_e32 vcc, 0, v1
	s_waitcnt lgkmcnt(0)
	s_waitcnt vmcnt(0)
	s_barrier
	s_and_saveexec_b64 s[4:5], vcc
	s_cbranch_execz .LBB0_353
	buffer_wbl2 sc1
	s_waitcnt vmcnt(0)
	s_load_dwordx2 s[8:9], s[0:1], 0xc8
	s_load_dword s3, s[0:1], 0x1b8
	s_and_b32 s10, s2, 7
	v_mov_b32_e32 v2, 1
	s_waitcnt lgkmcnt(0)
	s_add_u32 s8, s8, 0x2a4000
	s_addc_u32 s9, s9, 0
	s_sub_u32 s12, s3, s10
	s_add_u32 s12, s12, 7
	s_lshr_b32 s12, s12, 3
	s_mul_i32 s12, s12, 4
	s_min_u32 s3, s3, 8
	s_mul_i32 s3, s3, 2
	s_lshl_b32 s10, s10, 10
	v_mov_b32_e32 v1, s10
	global_atomic_add v3, v1, v2, s[8:9] sc0
	s_waitcnt vmcnt(0)
	v_readfirstlane_b32 s11, v3
	s_nop 3
	s_add_u32 s11, s11, 1
	s_cmp_lg_u32 s11, s12
	s_cbranch_scc1 .Lfs_wait_5
	s_branch .Lfs_grel_5
	v_mov_b32_e32 v1, 0x4000
	global_atomic_add v3, v1, v2, s[8:9] sc0
	s_waitcnt vmcnt(0)
	v_readfirstlane_b32 s11, v3
	s_nop 3
	s_add_u32 s11, s11, 1
	v_mov_b32_e32 v1, 0x5000
	s_cmp_lg_u32 s11, s3
	s_cbranch_scc1 .Lfs_topspin_5
	global_atomic_add v1, v2, s[8:9]
	s_branch .Lfs_grel_5

.LBB0_378:
.LBB0_379:
	v_and_b32_e32 v1, 0x3fffffff, v0
	v_cmp_eq_u32_e32 vcc, 0, v1
	s_waitcnt lgkmcnt(0)
	s_waitcnt vmcnt(0)
	s_barrier
	s_and_saveexec_b64 s[4:5], vcc
	s_cbranch_execz .LBB0_389
	buffer_wbl2 sc1
	s_waitcnt vmcnt(0)
	s_load_dwordx2 s[6:7], s[0:1], 0xc8
	s_load_dword s3, s[0:1], 0x1b8
	s_and_b32 s8, s2, 7
	v_mov_b32_e32 v2, 1
	s_waitcnt lgkmcnt(0)
	s_add_u32 s6, s6, 0x2a4000
	s_addc_u32 s7, s7, 0
	s_sub_u32 s12, s3, s8
	s_add_u32 s12, s12, 7
	s_lshr_b32 s12, s12, 3
	s_mul_i32 s12, s12, 5
	s_min_u32 s3, s3, 8
	s_mul_i32 s3, s3, 3
	s_lshl_b32 s8, s8, 10
	v_mov_b32_e32 v1, s8
	global_atomic_add v3, v1, v2, s[6:7] sc0
	s_waitcnt vmcnt(0)
	v_readfirstlane_b32 s9, v3
	s_nop 3
	s_add_u32 s9, s9, 1
	s_cmp_lg_u32 s9, s12
	s_cbranch_scc1 .Lfs_wait_6
	v_mov_b32_e32 v1, 0x4000
	global_atomic_add v3, v1, v2, s[6:7] sc0
	s_waitcnt vmcnt(0)
	v_readfirstlane_b32 s9, v3
	s_nop 3
	s_add_u32 s9, s9, 1
	v_mov_b32_e32 v1, 0x5000
	s_cmp_lg_u32 s9, s3
	s_cbranch_scc1 .Lfs_topspin_6
	global_atomic_add v1, v2, s[6:7]
	s_branch .Lfs_grel_6
.Lfs_topspin_6:
	s_sleep 1
	global_load_dword v3, v1, s[6:7] sc1
	s_waitcnt vmcnt(0)
	v_readfirstlane_b32 s9, v3
	s_nop 3
	s_cmp_lt_u32 s9, 3
	s_cbranch_scc1 .Lfs_topspin_6

.LBB0_457:
	v_and_b32_e32 v1, 0x3fffffff, v0
	v_cmp_eq_u32_e32 vcc, 0, v1
	s_waitcnt vmcnt(0)
	s_barrier
	s_and_saveexec_b64 s[4:5], vcc
	s_cbranch_execz .LBB0_467
	buffer_wbl2 sc1
	s_waitcnt vmcnt(0)
	s_load_dwordx2 s[6:7], s[0:1], 0xc8
	s_load_dword s3, s[0:1], 0x1b8
	s_and_b32 s8, s2, 7
	v_mov_b32_e32 v2, 1
	s_waitcnt lgkmcnt(0)
	s_add_u32 s6, s6, 0x2a4000
	s_addc_u32 s7, s7, 0
	s_sub_u32 s10, s3, s8
	s_add_u32 s10, s10, 7
	s_lshr_b32 s10, s10, 3
	s_mul_i32 s10, s10, 6
	s_min_u32 s3, s3, 8
	s_mul_i32 s3, s3, 4
	s_lshl_b32 s8, s8, 10
	v_mov_b32_e32 v1, s8
	global_atomic_add v3, v1, v2, s[6:7] sc0
	s_waitcnt vmcnt(0)
	v_readfirstlane_b32 s9, v3
	s_nop 3
	s_add_u32 s9, s9, 1
	s_cmp_lg_u32 s9, s10
	s_cbranch_scc1 .Lfs_wait_7
	v_mov_b32_e32 v1, 0x4000
	global_atomic_add v3, v1, v2, s[6:7] sc0
	s_waitcnt vmcnt(0)
	v_readfirstlane_b32 s9, v3
	s_nop 3
	s_add_u32 s9, s9, 1
	v_mov_b32_e32 v1, 0x5000
	s_cmp_lg_u32 s9, s3
	s_cbranch_scc1 .Lfs_topspin_7
	global_atomic_add v1, v2, s[6:7]
	s_branch .Lfs_grel_7
.Lfs_topspin_7:
	s_sleep 1
	global_load_dword v3, v1, s[6:7] sc1
	s_waitcnt vmcnt(0)
	v_readfirstlane_b32 s9, v3
	s_nop 3
	s_cmp_lt_u32 s9, 4
	s_cbranch_scc1 .Lfs_topspin_7

.LBB0_548:
.LBB0_549:
	v_and_b32_e32 v1, 0x3fffffff, v0
	v_cmp_eq_u32_e32 vcc, 0, v1
	s_waitcnt vmcnt(0)
	s_barrier
	s_and_saveexec_b64 s[4:5], vcc
	s_cbranch_execz .LBB0_559
	buffer_wbl2 sc1
	s_waitcnt vmcnt(0)
	s_load_dwordx2 s[8:9], s[0:1], 0xc8
	s_load_dword s3, s[0:1], 0x1b8
	s_and_b32 s10, s2, 7
	v_mov_b32_e32 v2, 1
	s_waitcnt lgkmcnt(0)
	s_add_u32 s8, s8, 0x2a4000
	s_addc_u32 s9, s9, 0
	s_sub_u32 s12, s3, s10
	s_add_u32 s12, s12, 7
	s_lshr_b32 s12, s12, 3
	s_mul_i32 s12, s12, 7
	s_min_u32 s3, s3, 8
	s_mul_i32 s3, s3, 5
	s_lshl_b32 s10, s10, 10
	v_mov_b32_e32 v1, s10
	global_atomic_add v3, v1, v2, s[8:9] sc0
	s_waitcnt vmcnt(0)
	v_readfirstlane_b32 s11, v3
	s_nop 3
	s_add_u32 s11, s11, 1
	s_cmp_lg_u32 s11, s12
	s_cbranch_scc1 .Lfs_wait_8
	v_mov_b32_e32 v1, 0x4000
	global_atomic_add v3, v1, v2, s[8:9] sc0
	s_waitcnt vmcnt(0)
	v_readfirstlane_b32 s11, v3
	s_nop 3
	s_add_u32 s11, s11, 1
	v_mov_b32_e32 v1, 0x5000
	s_cmp_lg_u32 s11, s3
	s_cbranch_scc1 .Lfs_topspin_8
	global_atomic_add v1, v2, s[8:9]
	s_branch .Lfs_grel_8
.Lfs_topspin_8:
	s_sleep 1
	global_load_dword v3, v1, s[8:9] sc1
	s_waitcnt vmcnt(0)
	v_readfirstlane_b32 s11, v3
	s_nop 3
	s_cmp_lt_u32 s11, 5
	s_cbranch_scc1 .Lfs_topspin_8

.LBB0_576:
.LBB0_577:
	v_and_b32_e32 v1, 0x3fffffff, v0
	v_cmp_eq_u32_e32 vcc, 0, v1
	s_waitcnt vmcnt(0)
	s_barrier
	s_and_saveexec_b64 s[6:7], vcc
	s_cbranch_execz .LBB0_587
	buffer_wbl2 sc1
	s_waitcnt vmcnt(0)
	s_load_dwordx2 s[8:9], s[0:1], 0xc8
	s_load_dword s3, s[0:1], 0x1b8
	s_and_b32 s10, s2, 7
	v_mov_b32_e32 v2, 1
	s_waitcnt lgkmcnt(0)
	s_add_u32 s8, s8, 0x2a4000
	s_addc_u32 s9, s9, 0
	s_sub_u32 s12, s3, s10
	s_add_u32 s12, s12, 7
	s_lshr_b32 s12, s12, 3
	s_mul_i32 s12, s12, 8
	s_min_u32 s3, s3, 8
	s_mul_i32 s3, s3, 5
	s_lshl_b32 s10, s10, 10
	v_mov_b32_e32 v1, s10
	global_atomic_add v3, v1, v2, s[8:9] sc0
	s_waitcnt vmcnt(0)
	v_readfirstlane_b32 s11, v3
	s_nop 3
	s_add_u32 s11, s11, 1
	s_cmp_lg_u32 s11, s12
	s_cbranch_scc1 .Lfs_wait_9
	s_branch .Lfs_grel_9
	v_mov_b32_e32 v1, 0x4000
	global_atomic_add v3, v1, v2, s[8:9] sc0
	s_waitcnt vmcnt(0)
	v_readfirstlane_b32 s11, v3
	s_nop 3
	s_add_u32 s11, s11, 1
	v_mov_b32_e32 v1, 0x5000
	s_cmp_lg_u32 s11, s3
	s_cbranch_scc1 .Lfs_topspin_9
	global_atomic_add v1, v2, s[8:9]
	s_branch .Lfs_grel_9

.LBB0_594:
.LBB0_595:
	v_and_b32_e32 v1, 0x3fffffff, v0
	v_cmp_eq_u32_e32 vcc, 0, v1
	s_waitcnt vmcnt(0)
	s_barrier
	s_and_saveexec_b64 s[4:5], vcc
	s_cbranch_execz .LBB0_605
	buffer_wbl2 sc1
	s_waitcnt vmcnt(0)
	s_load_dwordx2 s[6:7], s[0:1], 0xc8
	s_load_dword s3, s[0:1], 0x1b8
	s_and_b32 s8, s2, 7
	v_mov_b32_e32 v2, 1
	s_waitcnt lgkmcnt(0)
	s_add_u32 s6, s6, 0x2a4000
	s_addc_u32 s7, s7, 0
	s_sub_u32 s10, s3, s8
	s_add_u32 s10, s10, 7
	s_lshr_b32 s10, s10, 3
	s_mul_i32 s10, s10, 9
	s_min_u32 s3, s3, 8
	s_mul_i32 s3, s3, 5
	s_lshl_b32 s8, s8, 10
	v_mov_b32_e32 v1, s8
	global_atomic_add v3, v1, v2, s[6:7] sc0
	s_waitcnt vmcnt(0)
	v_readfirstlane_b32 s9, v3
	s_nop 3
	s_add_u32 s9, s9, 1
	s_cmp_lg_u32 s9, s10
	s_cbranch_scc1 .Lfs_wait_10
	s_branch .Lfs_grel_10
	v_mov_b32_e32 v1, 0x4000
	global_atomic_add v3, v1, v2, s[6:7] sc0
	s_waitcnt vmcnt(0)
	v_readfirstlane_b32 s9, v3
	s_nop 3
	s_add_u32 s9, s9, 1
	v_mov_b32_e32 v1, 0x5000
	s_cmp_lg_u32 s9, s3
	s_cbranch_scc1 .Lfs_topspin_10
	global_atomic_add v1, v2, s[6:7]
	s_branch .Lfs_grel_10
.Lfs_topspin_10:
	s_sleep 1
	global_load_dword v3, v1, s[6:7] sc1
	s_waitcnt vmcnt(0)
	v_readfirstlane_b32 s9, v3
	s_nop 3
	s_cmp_lt_u32 s9, 5
	s_cbranch_scc1 .Lfs_topspin_10
.Lfs_grel_10:
	s_add_u32 s11, s8, 0x8000
	v_mov_b32_e32 v1, s11
	global_atomic_add v1, v2, s[6:7]
	s_branch .Lfs_done_10
